# DF late loop: K fragment reads requested after the last V fragment pair so the first P.V MFMA waits for 2 reads not 10 (4-bit lgkmcnt); on top of hand-over trim
# speedup vs baseline: 1.0007x; 1.0007x over previous
.LBB0_408:
	s_andn2_b64 vcc, exec, s[10:11]
	s_cbranch_vccnz .LBB0_410
	s_lshl_b32 s10, s24, 14
	s_addk_i32 s10, 0xc000
	s_cmp_gt_i32 s24, 0
	s_cselect_b32 s10, s10, 0x10000
	v_add_u32_e32 v203, s10, v221
	s_nop 4
	ds_read_b64_tr_b16 v[80:81], v203
	ds_read_b64_tr_b16 v[82:83], v203 offset:512
	ds_read_b64_tr_b16 v[84:85], v203 offset:1024
	ds_read_b64_tr_b16 v[86:87], v203 offset:1536
	ds_read_b64_tr_b16 v[88:89], v203 offset:4096
	ds_read_b64_tr_b16 v[90:91], v203 offset:4608
	ds_read_b64_tr_b16 v[92:93], v203 offset:5120
	ds_read_b64_tr_b16 v[94:95], v203 offset:5632
	ds_read_b64_tr_b16 v[96:97], v203 offset:2048
	ds_read_b64_tr_b16 v[98:99], v203 offset:2560
	ds_read_b64_tr_b16 v[100:101], v203 offset:3072
	ds_read_b64_tr_b16 v[102:103], v203 offset:3584
	ds_read_b64_tr_b16 v[104:105], v203 offset:6144
	ds_read_b64_tr_b16 v[106:107], v203 offset:6656
	ds_read_b64_tr_b16 v[108:109], v203 offset:7168
	ds_read_b64_tr_b16 v[110:111], v203 offset:7680
	s_waitcnt lgkmcnt(14)
	v_mfma_f32_32x32x16_bf16 v[64:79], v[80:83], v[144:147], v[64:79]
	ds_read_b64_tr_b16 v[80:81], v203 offset:8192
	ds_read_b64_tr_b16 v[82:83], v203 offset:8704
	s_waitcnt lgkmcnt(12)
	v_mfma_f32_32x32x16_bf16 v[48:63], v[88:91], v[144:147], v[48:63]
	ds_read_b64_tr_b16 v[88:89], v203 offset:12288
	ds_read_b64_tr_b16 v[90:91], v203 offset:12800
	v_mfma_f32_32x32x16_bf16 v[64:79], v[84:87], v[10:13], v[64:79]
	ds_read_b64_tr_b16 v[84:85], v203 offset:9216
	ds_read_b64_tr_b16 v[86:87], v203 offset:9728
	s_waitcnt lgkmcnt(14)
	v_mfma_f32_32x32x16_bf16 v[48:63], v[92:95], v[10:13], v[48:63]
	ds_read_b64_tr_b16 v[92:93], v203 offset:13312
	ds_read_b64_tr_b16 v[94:95], v203 offset:13824
	s_waitcnt lgkmcnt(14)
	v_mfma_f32_32x32x16_bf16 v[64:79], v[96:99], v[6:9], v[64:79]
	ds_read_b64_tr_b16 v[96:97], v203 offset:10240
	ds_read_b64_tr_b16 v[98:99], v203 offset:10752
	s_waitcnt lgkmcnt(12)
	v_mfma_f32_32x32x16_bf16 v[48:63], v[104:107], v[6:9], v[48:63]
	ds_read_b64_tr_b16 v[104:105], v203 offset:14336
	ds_read_b64_tr_b16 v[106:107], v203 offset:14848
	v_mfma_f32_32x32x16_bf16 v[64:79], v[100:103], v[2:5], v[64:79]
	ds_read_b64_tr_b16 v[100:101], v203 offset:11264
	ds_read_b64_tr_b16 v[102:103], v203 offset:11776
	s_waitcnt lgkmcnt(14)
	v_mfma_f32_32x32x16_bf16 v[48:63], v[108:111], v[2:5], v[48:63]
	ds_read_b64_tr_b16 v[108:109], v203 offset:15360
	ds_read_b64_tr_b16 v[110:111], v203 offset:15872
	ds_read_b128 v[204:207], v202
	ds_read_b128 v[208:211], v202 offset:4096
	ds_read_b128 v[212:215], v15
	ds_read_b128 v[238:241], v15 offset:4096
	ds_read_b128 v[242:245], v14
	v_mov_b32_e32 v202, v246
	ds_read_b128 v[246:249], v14 offset:4096
	ds_read_b128 v[250:253], v0
	ds_read_b128 v[148:151], v0 offset:4096
	s_waitcnt lgkmcnt(15)
	v_mfma_f32_32x32x16_bf16 v[32:47], v[80:83], v[144:147], v[32:47]
	v_mfma_f32_32x32x16_bf16 v[16:31], v[88:91], v[144:147], v[16:31]
	v_mfma_f32_32x32x16_bf16 v[32:47], v[84:87], v[10:13], v[32:47]
	v_mfma_f32_32x32x16_bf16 v[16:31], v[92:95], v[10:13], v[16:31]
	s_waitcnt lgkmcnt(14)
	v_mfma_f32_32x32x16_bf16 v[32:47], v[96:99], v[6:9], v[32:47]
	s_waitcnt lgkmcnt(12)
	v_mfma_f32_32x32x16_bf16 v[16:31], v[104:107], v[6:9], v[16:31]
	s_waitcnt lgkmcnt(10)
	v_mfma_f32_32x32x16_bf16 v[32:47], v[100:103], v[2:5], v[32:47]
	s_waitcnt lgkmcnt(8)
	v_mfma_f32_32x32x16_bf16 v[16:31], v[108:111], v[2:5], v[16:31]
	s_waitcnt lgkmcnt(7)
	v_mfma_f32_32x32x16_bf16 v[96:111], v[204:207], v[136:139], 0
	s_waitcnt lgkmcnt(6)
	v_mfma_f32_32x32x16_bf16 v[80:95], v[208:211], v[136:139], 0
	s_waitcnt lgkmcnt(5)
	v_mfma_f32_32x32x16_bf16 v[96:111], v[212:215], v[128:131], v[96:111]
	s_waitcnt lgkmcnt(4)
	v_mfma_f32_32x32x16_bf16 v[80:95], v[238:241], v[128:131], v[80:95]
	s_waitcnt lgkmcnt(3)
	v_mfma_f32_32x32x16_bf16 v[96:111], v[242:245], v[140:143], v[96:111]
	s_waitcnt lgkmcnt(2)
	v_mfma_f32_32x32x16_bf16 v[80:95], v[246:249], v[140:143], v[80:95]
	v_mov_b32_e32 v246, v202
	s_waitcnt lgkmcnt(1)
	v_mfma_f32_32x32x16_bf16 v[96:111], v[250:253], v[132:135], v[96:111]
	s_waitcnt lgkmcnt(0)
	v_mfma_f32_32x32x16_bf16 v[80:95], v[148:151], v[132:135], v[80:95]
